# first grid-barrier census: the sixteen per-XCD counter loads issued together
# speedup vs baseline: 1.0112x; 1.0112x over previous
; __device__ __forceinline__ unsigned xb_ld(unsigned* p)              { return __hip_atomic_load(p, __ATOMIC_RELAXED, __HIP_MEMORY_SCOPE_AGENT); }
; __device__ __forceinline__ void xcd_barrier_complete(unsigned* bar, unsigned x, unsigned& nloc, unsigned& nx) {
;     const unsigned G = gridDim.x * gridDim.y * gridDim.z;
;     unsigned sum, cnt, mine, sp = 0u;
;     for (;;) {
;         sum = 0u; cnt = 0u; mine = 0u;
; #pragma unroll
;         for (unsigned j = 0; j < 16; ++j) { const unsigned c = xb_ld(&bar[XB_XCNT(j)]); sum += c; cnt += (c > 0u) ? 1u : 0u; mine = (j == x) ? c : mine; }
;         if (sum == G) break;
;         __builtin_amdgcn_s_sleep(1);
;         if ((++sp & 255u) == 0u) { if (xb_ld(&bar[XB_TMO])) break; if (sp > XB_SPIN_CAP) { atomicAdd(&bar[XB_TMO], 1u); break; } }
;     }
;     nloc = mine > 0u ? mine : 1u; nx = cnt > 0u ? cnt : 1u;
; }
.LBB0_893:
	v_readlane_b32 s8, v251, 34
	v_readlane_b32 s9, v251, 35
	s_mov_b64 s[10:11], -1
	s_nop 3
	global_load_dword v0, v165, s[8:9] sc1
	global_load_dword v1, v165, s[8:9] offset:256 sc1
	global_load_dword v2, v165, s[8:9] offset:512 sc1
	global_load_dword v3, v165, s[8:9] offset:768 sc1
	global_load_dword v4, v165, s[8:9] offset:1024 sc1
	global_load_dword v5, v165, s[8:9] offset:1280 sc1
	global_load_dword v6, v165, s[8:9] offset:1536 sc1
	global_load_dword v7, v165, s[8:9] offset:1792 sc1
	global_load_dword v8, v165, s[8:9] offset:2048 sc1
	global_load_dword v9, v165, s[8:9] offset:2304 sc1
	global_load_dword v10, v165, s[8:9] offset:2560 sc1
	global_load_dword v11, v165, s[8:9] offset:2816 sc1
	global_load_dword v12, v165, s[8:9] offset:3072 sc1
	global_load_dword v13, v165, s[8:9] offset:3328 sc1
	global_load_dword v14, v165, s[8:9] offset:3584 sc1
	global_load_dword v15, v165, s[8:9] offset:3840 sc1
	s_mov_b64 s[8:9], -1
	s_waitcnt vmcnt(0)
	v_add_u32_e32 v16, v1, v0
	v_add_u32_e32 v16, v16, v2
	v_add_u32_e32 v16, v16, v3
	v_add_u32_e32 v16, v16, v4
	v_add_u32_e32 v16, v16, v5
	v_add_u32_e32 v16, v16, v6
	v_add_u32_e32 v16, v16, v7
	v_add_u32_e32 v16, v16, v8
	v_add_u32_e32 v16, v16, v9
	v_add_u32_e32 v16, v16, v10
	v_add_u32_e32 v16, v16, v11
	v_add_u32_e32 v16, v16, v12
	v_add_u32_e32 v16, v16, v13
	v_add_u32_e32 v16, v16, v14
	v_add_u32_e32 v16, v16, v15
	v_cmp_eq_u32_e32 vcc, s6, v16
	s_cbranch_vccnz .LBB0_892
	s_and_b32 s8, s7, 0xff
	s_cmp_eq_u32 s8, 0
	s_mov_b64 s[8:9], -1
	s_mov_b64 s[12:13], -1
	s_sleep 1
	s_cbranch_scc1 .LBB0_897
	s_and_b64 vcc, exec, s[12:13]
	s_cbranch_vccz .LBB0_892
